# P6 side conversion: its bf16 weight stores written through (sc1) so they do not sit dirty in the L2 the GEMM members share
# speedup vs baseline: 1.0085x; 1.0085x over previous
.LBB0_963:
	s_cmpk_gt_i32 s3, 0x1ff
	s_mov_b64 s[14:15], -1
	s_cbranch_scc0 .LBB0_969
	s_cmpk_gt_u32 s3, 0x9ff
	s_cbranch_scc0 .LBB0_966
	s_and_b32 s8, s5, 0x7fffffc0
	s_and_b32 s14, s4, 0x3e0
	v_or_b32_e32 v2, s8, v12
	v_or_b32_e32 v28, s14, v1
	v_lshlrev_b64 v[26:27], 12, v[2:3]
	v_lshl_add_u64 v[26:27], s[10:11], 0, v[26:27]
	v_lshlrev_b32_e32 v2, 2, v28
	v_lshl_add_u64 v[26:27], v[26:27], 0, v[2:3]
	v_add_co_u32_e32 v28, vcc, 0x2000, v26
	s_lshl_b32 s8, s8, 1
	s_nop 0
	v_addc_co_u32_e32 v29, vcc, 0, v27, vcc
	v_add_co_u32_e32 v30, vcc, 0x4000, v26
	s_nop 1
	v_addc_co_u32_e32 v31, vcc, 0, v27, vcc
	v_add_co_u32_e32 v32, vcc, 0x6000, v26
	s_nop 1
	v_addc_co_u32_e32 v33, vcc, 0, v27, vcc
	v_add_co_u32_e32 v34, vcc, 0x8000, v26
	s_nop 1
	v_addc_co_u32_e32 v35, vcc, 0, v27, vcc
	v_add_co_u32_e32 v36, vcc, 0xa000, v26
	s_nop 1
	v_addc_co_u32_e32 v37, vcc, 0, v27, vcc
	v_add_co_u32_e32 v38, vcc, 0xc000, v26
	s_nop 1
	v_addc_co_u32_e32 v39, vcc, 0, v27, vcc
	v_add_co_u32_e32 v40, vcc, 0xe000, v26
	s_nop 1
	v_addc_co_u32_e32 v41, vcc, 0, v27, vcc
	global_load_dword v2, v[26:27], off nt
	global_load_dword v44, v[28:29], off nt
	global_load_dword v45, v[30:31], off nt
	global_load_dword v46, v[32:33], off nt
	global_load_dword v47, v[34:35], off nt
	global_load_dword v48, v[36:37], off nt
	global_load_dword v49, v[38:39], off nt
	global_load_dword v50, v[40:41], off nt
	v_add_co_u32_e32 v28, vcc, 0x10000, v26
	s_nop 1
	v_addc_co_u32_e32 v29, vcc, 0, v27, vcc
	v_add_co_u32_e32 v30, vcc, 0x12000, v26
	s_nop 1
	v_addc_co_u32_e32 v31, vcc, 0, v27, vcc
	v_add_co_u32_e32 v32, vcc, 0x14000, v26
	s_nop 1
	v_addc_co_u32_e32 v33, vcc, 0, v27, vcc
	v_add_co_u32_e32 v34, vcc, 0x16000, v26
	s_nop 1
	v_addc_co_u32_e32 v35, vcc, 0, v27, vcc
	v_add_co_u32_e32 v36, vcc, 0x18000, v26
	s_nop 1
	v_addc_co_u32_e32 v37, vcc, 0, v27, vcc
	v_add_co_u32_e32 v38, vcc, 0x1a000, v26
	s_nop 1
	v_addc_co_u32_e32 v39, vcc, 0, v27, vcc
	v_add_co_u32_e32 v40, vcc, 0x1c000, v26
	s_nop 1
	v_addc_co_u32_e32 v41, vcc, 0, v27, vcc
	v_add_co_u32_e32 v42, vcc, 0x1e000, v26
	s_nop 1
	v_addc_co_u32_e32 v43, vcc, 0, v27, vcc
	global_load_dword v51, v[28:29], off nt
	global_load_dword v52, v[30:31], off nt
	global_load_dword v53, v[32:33], off nt
	global_load_dword v54, v[34:35], off nt
	global_load_dword v55, v[36:37], off nt
	global_load_dword v56, v[38:39], off nt
	global_load_dword v57, v[40:41], off nt
	global_load_dword v58, v[42:43], off nt
	v_add_co_u32_e32 v28, vcc, 0x20000, v26
	s_nop 1
	v_addc_co_u32_e32 v29, vcc, 0, v27, vcc
	v_add_co_u32_e32 v30, vcc, 0x22000, v26
	s_nop 1
	v_addc_co_u32_e32 v31, vcc, 0, v27, vcc
	v_add_co_u32_e32 v32, vcc, 0x24000, v26
	s_nop 1
	v_addc_co_u32_e32 v33, vcc, 0, v27, vcc
	v_add_co_u32_e32 v34, vcc, 0x26000, v26
	s_nop 1
	v_addc_co_u32_e32 v35, vcc, 0, v27, vcc
	v_add_co_u32_e32 v36, vcc, 0x28000, v26
	s_nop 1
	v_addc_co_u32_e32 v37, vcc, 0, v27, vcc
	v_add_co_u32_e32 v38, vcc, 0x2a000, v26
	s_nop 1
	v_addc_co_u32_e32 v39, vcc, 0, v27, vcc
	v_add_co_u32_e32 v40, vcc, 0x2c000, v26
	s_nop 1
	v_addc_co_u32_e32 v41, vcc, 0, v27, vcc
	v_add_co_u32_e32 v42, vcc, 0x2e000, v26
	s_nop 1
	v_addc_co_u32_e32 v43, vcc, 0, v27, vcc
	global_load_dword v59, v[28:29], off nt
	global_load_dword v60, v[30:31], off nt
	global_load_dword v61, v[32:33], off nt
	global_load_dword v62, v[34:35], off nt
	global_load_dword v63, v[36:37], off nt
	global_load_dword v64, v[38:39], off nt
	global_load_dword v65, v[40:41], off nt
	s_nop 0
	global_load_dword v42, v[42:43], off nt
	v_add_co_u32_e32 v28, vcc, 0x30000, v26
	s_nop 1
	v_addc_co_u32_e32 v29, vcc, 0, v27, vcc
	v_add_co_u32_e32 v30, vcc, 0x32000, v26
	s_nop 1
	v_addc_co_u32_e32 v31, vcc, 0, v27, vcc
	v_add_co_u32_e32 v32, vcc, 0x34000, v26
	s_nop 1
	v_addc_co_u32_e32 v33, vcc, 0, v27, vcc
	v_add_co_u32_e32 v34, vcc, 0x36000, v26
	s_nop 1
	v_addc_co_u32_e32 v35, vcc, 0, v27, vcc
	v_add_co_u32_e32 v36, vcc, 0x38000, v26
	s_nop 1
	v_addc_co_u32_e32 v37, vcc, 0, v27, vcc
	v_add_co_u32_e32 v38, vcc, 0x3a000, v26
	s_nop 1
	v_addc_co_u32_e32 v39, vcc, 0, v27, vcc
	v_add_co_u32_e32 v40, vcc, 0x3c000, v26
	s_nop 1
	v_addc_co_u32_e32 v41, vcc, 0, v27, vcc
	v_add_co_u32_e32 v26, vcc, 0x3e000, v26
	s_nop 1
	v_addc_co_u32_e32 v27, vcc, 0, v27, vcc
	global_load_dword v28, v[28:29], off nt
	s_nop 0
	global_load_dword v29, v[30:31], off nt
	s_nop 0
	global_load_dword v30, v[32:33], off nt
	global_load_dword v31, v[34:35], off nt
	s_nop 0
	global_load_dword v32, v[36:37], off nt
	global_load_dword v33, v[38:39], off nt
	global_load_dword v34, v[40:41], off nt
	s_nop 0
	global_load_dword v26, v[26:27], off nt
	s_waitcnt vmcnt(30)
	ds_write2_b32 v13, v2, v44 offset1:66
	s_waitcnt vmcnt(28)
	ds_write2_b32 v13, v45, v46 offset0:132 offset1:198
	s_waitcnt vmcnt(26)
	ds_write2_b32 v19, v47, v48 offset0:8 offset1:74
	s_waitcnt vmcnt(24)
	ds_write2_b32 v19, v49, v50 offset0:140 offset1:206
	s_waitcnt vmcnt(22)
	ds_write2_b32 v20, v51, v52 offset0:16 offset1:82
	s_waitcnt vmcnt(20)
	ds_write2_b32 v20, v53, v54 offset0:148 offset1:214
	s_waitcnt vmcnt(18)
	ds_write2_b32 v21, v55, v56 offset0:24 offset1:90
	s_waitcnt vmcnt(16)
	ds_write2_b32 v21, v57, v58 offset0:156 offset1:222
	s_waitcnt vmcnt(14)
	ds_write2_b32 v22, v59, v60 offset0:32 offset1:98
	s_waitcnt vmcnt(12)
	ds_write2_b32 v22, v61, v62 offset0:164 offset1:230
	s_waitcnt vmcnt(10)
	ds_write2_b32 v23, v63, v64 offset0:40 offset1:106
	s_waitcnt vmcnt(8)
	ds_write2_b32 v23, v65, v42 offset0:172 offset1:238
	s_waitcnt vmcnt(6)
	ds_write2_b32 v24, v28, v29 offset0:48 offset1:114
	s_waitcnt vmcnt(4)
	ds_write2_b32 v24, v30, v31 offset0:180 offset1:246
	s_waitcnt vmcnt(2)
	ds_write2_b32 v25, v32, v33 offset0:56 offset1:122
	s_waitcnt vmcnt(0)
	ds_write2_b32 v25, v34, v26 offset0:188 offset1:254
	s_waitcnt lgkmcnt(0)
	ds_read2_b32 v[30:31], v15 offset1:8
	ds_read2_b32 v[34:35], v15 offset0:33 offset1:41
	ds_read2_b32 v[36:37], v15 offset0:66 offset1:74
	ds_read2_b32 v[38:39], v15 offset0:99 offset1:107
	ds_read2_b32 v[40:41], v15 offset0:132 offset1:140
	s_waitcnt lgkmcnt(4)
	v_bfe_u32 v2, v30, 16, 1
	v_add3_u32 v2, v30, v2, s52
	s_waitcnt lgkmcnt(3)
	v_bfe_u32 v26, v34, 16, 1
	v_lshrrev_b32_e32 v2, 16, v2
	v_add3_u32 v26, v34, v26, s52
	ds_read2_b32 v[42:43], v15 offset0:165 offset1:173
	v_and_or_b32 v26, v26, s53, v2
	s_waitcnt lgkmcnt(3)
	v_bfe_u32 v2, v36, 16, 1
	v_add3_u32 v2, v36, v2, s52
	s_waitcnt lgkmcnt(2)
	v_bfe_u32 v27, v38, 16, 1
	ds_read2_b32 v[44:45], v15 offset0:198 offset1:206
	v_lshrrev_b32_e32 v2, 16, v2
	v_add3_u32 v27, v38, v27, s52
	ds_read2_b32 v[46:47], v15 offset0:231 offset1:239
	v_and_or_b32 v27, v27, s53, v2
	s_waitcnt lgkmcnt(3)
	v_bfe_u32 v2, v40, 16, 1
	v_add3_u32 v2, v40, v2, s52
	s_waitcnt lgkmcnt(2)
	v_bfe_u32 v28, v42, 16, 1
	v_lshrrev_b32_e32 v2, 16, v2
	v_add3_u32 v28, v42, v28, s52
	v_and_or_b32 v28, v28, s53, v2
	s_waitcnt lgkmcnt(1)
	v_bfe_u32 v2, v44, 16, 1
	v_add3_u32 v2, v44, v2, s52
	s_waitcnt lgkmcnt(0)
	v_bfe_u32 v29, v46, 16, 1
	v_lshrrev_b32_e32 v2, 16, v2
	v_add3_u32 v29, v46, v29, s52
	v_and_or_b32 v29, v29, s53, v2
	v_or_b32_e32 v2, s14, v14
	v_lshl_add_u64 v[32:33], v[4:5], 0, s[8:9]
	v_lshlrev_b32_e32 v2, 13, v2
	v_lshl_add_u64 v[48:49], v[32:33], 0, v[2:3]
	v_bfe_u32 v2, v31, 16, 1
	global_store_dwordx4 v[48:49], v[26:29], off sc1
	v_add3_u32 v2, v31, v2, s52
	v_lshrrev_b32_e32 v2, 16, v2
	v_bfe_u32 v26, v35, 16, 1
	v_add3_u32 v26, v35, v26, s52
	v_and_or_b32 v26, v26, s53, v2
	v_bfe_u32 v2, v37, 16, 1
	v_add3_u32 v2, v37, v2, s52
	v_bfe_u32 v27, v39, 16, 1
	v_lshrrev_b32_e32 v2, 16, v2
	v_add3_u32 v27, v39, v27, s52
	v_and_or_b32 v27, v27, s53, v2
	v_bfe_u32 v2, v41, 16, 1
	v_add3_u32 v2, v41, v2, s52
	v_bfe_u32 v28, v43, 16, 1
	v_lshrrev_b32_e32 v2, 16, v2
	v_add3_u32 v28, v43, v28, s52
	v_and_or_b32 v28, v28, s53, v2
	v_bfe_u32 v2, v45, 16, 1
	v_add3_u32 v2, v45, v2, s52
	v_bfe_u32 v29, v47, 16, 1
	v_lshrrev_b32_e32 v2, 16, v2
	v_add3_u32 v29, v47, v29, s52
	v_and_or_b32 v29, v29, s53, v2
	v_or_b32_e32 v2, s14, v16
	v_lshlrev_b32_e32 v2, 13, v2
	ds_read2_b32 v[30:31], v15 offset0:16 offset1:24
	v_lshl_add_u64 v[34:35], v[32:33], 0, v[2:3]
	global_store_dwordx4 v[34:35], v[26:29], off sc1
	ds_read2_b32 v[34:35], v15 offset0:49 offset1:57
	ds_read2_b32 v[36:37], v15 offset0:82 offset1:90
	ds_read2_b32 v[38:39], v15 offset0:115 offset1:123
	s_waitcnt lgkmcnt(3)
	v_bfe_u32 v2, v30, 16, 1
	v_add3_u32 v2, v30, v2, s52
	s_waitcnt lgkmcnt(2)
	v_bfe_u32 v26, v34, 16, 1
	ds_read2_b32 v[40:41], v15 offset0:148 offset1:156
	v_lshrrev_b32_e32 v2, 16, v2
	v_add3_u32 v26, v34, v26, s52
	ds_read2_b32 v[42:43], v15 offset0:181 offset1:189
	v_and_or_b32 v26, v26, s53, v2
	s_waitcnt lgkmcnt(3)
	v_bfe_u32 v2, v36, 16, 1
	v_add3_u32 v2, v36, v2, s52
	s_waitcnt lgkmcnt(2)
	v_bfe_u32 v27, v38, 16, 1
	ds_read2_b32 v[44:45], v15 offset0:214 offset1:222
	v_lshrrev_b32_e32 v2, 16, v2
	v_add3_u32 v27, v38, v27, s52
	ds_read2_b32 v[46:47], v15 offset0:247 offset1:255
	v_and_or_b32 v27, v27, s53, v2
	s_waitcnt lgkmcnt(3)
	v_bfe_u32 v2, v40, 16, 1
	v_add3_u32 v2, v40, v2, s52
	s_waitcnt lgkmcnt(2)
	v_bfe_u32 v28, v42, 16, 1
	v_lshrrev_b32_e32 v2, 16, v2
	v_add3_u32 v28, v42, v28, s52
	v_and_or_b32 v28, v28, s53, v2
	s_waitcnt lgkmcnt(1)
	v_bfe_u32 v2, v44, 16, 1
	v_add3_u32 v2, v44, v2, s52
	s_waitcnt lgkmcnt(0)
	v_bfe_u32 v29, v46, 16, 1
	v_lshrrev_b32_e32 v2, 16, v2
	v_add3_u32 v29, v46, v29, s52
	v_and_or_b32 v29, v29, s53, v2
	v_or_b32_e32 v2, s14, v17
	v_lshlrev_b32_e32 v2, 13, v2
	v_lshl_add_u64 v[48:49], v[32:33], 0, v[2:3]
	v_bfe_u32 v2, v31, 16, 1
	global_store_dwordx4 v[48:49], v[26:29], off sc1
	v_add3_u32 v2, v31, v2, s52
	v_lshrrev_b32_e32 v2, 16, v2
	v_bfe_u32 v26, v35, 16, 1
	v_add3_u32 v26, v35, v26, s52
	v_and_or_b32 v26, v26, s53, v2
	v_bfe_u32 v2, v37, 16, 1
	v_add3_u32 v2, v37, v2, s52
	v_bfe_u32 v27, v39, 16, 1
	v_lshrrev_b32_e32 v2, 16, v2
	v_add3_u32 v27, v39, v27, s52
	v_and_or_b32 v27, v27, s53, v2
	v_bfe_u32 v2, v41, 16, 1
	v_add3_u32 v2, v41, v2, s52
	v_bfe_u32 v28, v43, 16, 1
	v_lshrrev_b32_e32 v2, 16, v2
	v_add3_u32 v28, v43, v28, s52
	v_and_or_b32 v28, v28, s53, v2
	v_bfe_u32 v2, v45, 16, 1
	v_add3_u32 v2, v45, v2, s52
	v_bfe_u32 v29, v47, 16, 1
	v_lshrrev_b32_e32 v2, 16, v2
	v_add3_u32 v29, v47, v29, s52
	v_and_or_b32 v29, v29, s53, v2
	v_or_b32_e32 v2, s14, v18
	v_lshlrev_b32_e32 v2, 13, v2
	v_lshl_add_u64 v[30:31], v[32:33], 0, v[2:3]
	global_store_dwordx4 v[30:31], v[26:29], off sc1
	s_waitcnt lgkmcnt(0)
	s_mov_b64 s[14:15], 0
.LBB0_966:
	s_andn2_b64 vcc, exec, s[14:15]
	s_cbranch_vccnz .LBB0_968
	s_add_i32 s8, s3, 0xfffffe00
	s_lshr_b32 s8, s8, 1
	s_and_b32 s8, s8, 0x7fffffc0
	s_and_b32 s14, s4, 0xfe0
	v_or_b32_e32 v2, s8, v12
	v_or_b32_e32 v28, s14, v1
	v_lshlrev_b64 v[26:27], 14, v[2:3]
	v_lshl_add_u64 v[26:27], s[12:13], 0, v[26:27]
	v_lshlrev_b32_e32 v2, 2, v28
	v_lshl_add_u64 v[26:27], v[26:27], 0, v[2:3]
	v_add_co_u32_e32 v28, vcc, 0x8000, v26
	s_nop 1
	v_addc_co_u32_e32 v29, vcc, 0, v27, vcc
	v_add_co_u32_e32 v30, vcc, 0x10000, v26
	s_nop 1
	v_addc_co_u32_e32 v31, vcc, 0, v27, vcc
	v_add_co_u32_e32 v32, vcc, 0x18000, v26
	s_nop 1
	v_addc_co_u32_e32 v33, vcc, 0, v27, vcc
	v_add_co_u32_e32 v34, vcc, 0x20000, v26
	s_nop 1
	v_addc_co_u32_e32 v35, vcc, 0, v27, vcc
	v_add_co_u32_e32 v36, vcc, 0x28000, v26
	s_nop 1
	v_addc_co_u32_e32 v37, vcc, 0, v27, vcc
	v_add_co_u32_e32 v38, vcc, 0x30000, v26
	s_nop 1
	v_addc_co_u32_e32 v39, vcc, 0, v27, vcc
	v_add_co_u32_e32 v40, vcc, 0x38000, v26
	s_nop 1
	v_addc_co_u32_e32 v41, vcc, 0, v27, vcc
	global_load_dword v2, v[26:27], off nt
	global_load_dword v44, v[28:29], off nt
	global_load_dword v45, v[30:31], off nt
	global_load_dword v46, v[32:33], off nt
	global_load_dword v47, v[34:35], off nt
	global_load_dword v48, v[36:37], off nt
	global_load_dword v49, v[38:39], off nt
	global_load_dword v50, v[40:41], off nt
	v_add_co_u32_e32 v28, vcc, 0x40000, v26
	s_nop 1
	v_addc_co_u32_e32 v29, vcc, 0, v27, vcc
	v_add_co_u32_e32 v30, vcc, 0x48000, v26
	s_nop 1
	v_addc_co_u32_e32 v31, vcc, 0, v27, vcc
	v_add_co_u32_e32 v32, vcc, 0x50000, v26
	s_nop 1
	v_addc_co_u32_e32 v33, vcc, 0, v27, vcc
	v_add_co_u32_e32 v34, vcc, 0x58000, v26
	s_nop 1
	v_addc_co_u32_e32 v35, vcc, 0, v27, vcc
	v_add_co_u32_e32 v36, vcc, 0x60000, v26
	s_nop 1
	v_addc_co_u32_e32 v37, vcc, 0, v27, vcc
	v_add_co_u32_e32 v38, vcc, 0x68000, v26
	s_nop 1
	v_addc_co_u32_e32 v39, vcc, 0, v27, vcc
	v_add_co_u32_e32 v40, vcc, 0x70000, v26
	s_nop 1
	v_addc_co_u32_e32 v41, vcc, 0, v27, vcc
	v_add_co_u32_e32 v42, vcc, 0x78000, v26
	s_nop 1
	v_addc_co_u32_e32 v43, vcc, 0, v27, vcc
	global_load_dword v51, v[28:29], off nt
	global_load_dword v52, v[30:31], off nt
	global_load_dword v53, v[32:33], off nt
	global_load_dword v54, v[34:35], off nt
	global_load_dword v55, v[36:37], off nt
	global_load_dword v56, v[38:39], off nt
	global_load_dword v57, v[40:41], off nt
	global_load_dword v58, v[42:43], off nt
	v_add_co_u32_e32 v28, vcc, 0x80000, v26
	s_nop 1
	v_addc_co_u32_e32 v29, vcc, 0, v27, vcc
	v_add_co_u32_e32 v30, vcc, 0x88000, v26
	s_nop 1
	v_addc_co_u32_e32 v31, vcc, 0, v27, vcc
	v_add_co_u32_e32 v32, vcc, 0x90000, v26
	s_nop 1
	v_addc_co_u32_e32 v33, vcc, 0, v27, vcc
	v_add_co_u32_e32 v34, vcc, 0x98000, v26
	s_nop 1
	v_addc_co_u32_e32 v35, vcc, 0, v27, vcc
	v_add_co_u32_e32 v36, vcc, 0xa0000, v26
	s_nop 1
	v_addc_co_u32_e32 v37, vcc, 0, v27, vcc
	v_add_co_u32_e32 v38, vcc, 0xa8000, v26
	s_nop 1
	v_addc_co_u32_e32 v39, vcc, 0, v27, vcc
	v_add_co_u32_e32 v40, vcc, 0xb0000, v26
	s_nop 1
	v_addc_co_u32_e32 v41, vcc, 0, v27, vcc
	v_add_co_u32_e32 v42, vcc, 0xb8000, v26
	s_nop 1
	v_addc_co_u32_e32 v43, vcc, 0, v27, vcc
	global_load_dword v59, v[28:29], off nt
	global_load_dword v60, v[30:31], off nt
	global_load_dword v61, v[32:33], off nt
	global_load_dword v62, v[34:35], off nt
	global_load_dword v63, v[36:37], off nt
	global_load_dword v64, v[38:39], off nt
	global_load_dword v65, v[40:41], off nt
	s_nop 0
	global_load_dword v42, v[42:43], off nt
	v_add_co_u32_e32 v28, vcc, 0xc0000, v26
	s_nop 1
	v_addc_co_u32_e32 v29, vcc, 0, v27, vcc
	v_add_co_u32_e32 v30, vcc, 0xc8000, v26
	s_nop 1
	v_addc_co_u32_e32 v31, vcc, 0, v27, vcc
	v_add_co_u32_e32 v32, vcc, 0xd0000, v26
	s_nop 1
	v_addc_co_u32_e32 v33, vcc, 0, v27, vcc
	v_add_co_u32_e32 v34, vcc, 0xd8000, v26
	s_nop 1
	v_addc_co_u32_e32 v35, vcc, 0, v27, vcc
	v_add_co_u32_e32 v36, vcc, 0xe0000, v26
	s_nop 1
	v_addc_co_u32_e32 v37, vcc, 0, v27, vcc
	v_add_co_u32_e32 v38, vcc, 0xe8000, v26
	s_nop 1
	v_addc_co_u32_e32 v39, vcc, 0, v27, vcc
	v_add_co_u32_e32 v40, vcc, 0xf0000, v26
	s_nop 1
	v_addc_co_u32_e32 v41, vcc, 0, v27, vcc
	v_add_co_u32_e32 v26, vcc, 0xf8000, v26
	s_nop 1
	v_addc_co_u32_e32 v27, vcc, 0, v27, vcc
	global_load_dword v43, v[28:29], off nt
	global_load_dword v66, v[30:31], off nt
	global_load_dword v67, v[32:33], off nt
	s_nop 0
	global_load_dword v34, v[34:35], off nt
	s_nop 0
	global_load_dword v35, v[36:37], off nt
	s_nop 0
	global_load_dword v36, v[38:39], off nt
	global_load_dword v37, v[40:41], off nt
	s_nop 0
	global_load_dword v38, v[26:27], off nt
	v_lshl_add_u64 v[30:31], s[8:9], 2, v[6:7]
	global_load_dwordx4 v[26:29], v[30:31], off
	s_nop 0
	global_load_dwordx4 v[30:33], v[30:31], off offset:16
	s_waitcnt vmcnt(32)
	ds_write2_b32 v13, v2, v44 offset1:66
	s_waitcnt vmcnt(30)
	ds_write2_b32 v13, v45, v46 offset0:132 offset1:198
	s_waitcnt vmcnt(28)
	ds_write2_b32 v19, v47, v48 offset0:8 offset1:74
	s_waitcnt vmcnt(26)
	ds_write2_b32 v19, v49, v50 offset0:140 offset1:206
	s_waitcnt vmcnt(24)
	ds_write2_b32 v20, v51, v52 offset0:16 offset1:82
	s_waitcnt vmcnt(22)
	ds_write2_b32 v20, v53, v54 offset0:148 offset1:214
	s_waitcnt vmcnt(20)
	ds_write2_b32 v21, v55, v56 offset0:24 offset1:90
	s_waitcnt vmcnt(18)
	ds_write2_b32 v21, v57, v58 offset0:156 offset1:222
	s_waitcnt vmcnt(16)
	ds_write2_b32 v22, v59, v60 offset0:32 offset1:98
	s_waitcnt vmcnt(14)
	ds_write2_b32 v22, v61, v62 offset0:164 offset1:230
	s_waitcnt vmcnt(12)
	ds_write2_b32 v23, v63, v64 offset0:40 offset1:106
	s_waitcnt vmcnt(10)
	ds_write2_b32 v23, v65, v42 offset0:172 offset1:238
	s_waitcnt vmcnt(8)
	ds_write2_b32 v24, v43, v66 offset0:48 offset1:114
	s_waitcnt vmcnt(6)
	ds_write2_b32 v24, v67, v34 offset0:180 offset1:246
	s_waitcnt vmcnt(4)
	ds_write2_b32 v25, v35, v36 offset0:56 offset1:122
	s_waitcnt vmcnt(2)
	ds_write2_b32 v25, v37, v38 offset0:188 offset1:254
	s_waitcnt lgkmcnt(0)
	ds_read2_b32 v[40:41], v15 offset0:33 offset1:41
	ds_read2_b32 v[42:43], v15 offset1:8
	ds_read2_b32 v[44:45], v15 offset0:66 offset1:74
	ds_read2_b32 v[46:47], v15 offset0:99 offset1:107
	ds_read2_b32 v[50:51], v15 offset0:132 offset1:140
	ds_read2_b32 v[52:53], v15 offset0:165 offset1:173
	ds_read2_b32 v[54:55], v15 offset0:198 offset1:206
	ds_read2_b32 v[56:57], v15 offset0:231 offset1:239
	s_waitcnt vmcnt(1)
	v_mov_b32_e32 v48, v26
	v_mov_b32_e32 v49, v28
	v_mov_b32_e32 v28, v27
	s_waitcnt lgkmcnt(7)
	v_mov_b32_e32 v26, v40
	s_waitcnt lgkmcnt(4)
	v_mov_b32_e32 v27, v46
	s_waitcnt vmcnt(0)
	v_mov_b32_e32 v58, v30
	v_mov_b32_e32 v59, v32
	v_mov_b32_e32 v32, v31
	s_waitcnt lgkmcnt(2)
	v_mov_b32_e32 v30, v52
	s_waitcnt lgkmcnt(0)
	v_mov_b32_e32 v31, v56
	v_mov_b32_e32 v34, v42
	v_mov_b32_e32 v35, v44
	v_pk_mul_f32 v[26:27], v[28:29], v[26:27]
	v_mov_b32_e32 v36, v50
	v_mov_b32_e32 v37, v54
	v_pk_mul_f32 v[30:31], v[32:33], v[30:31]
	v_pk_mul_f32 v[34:35], v[48:49], v[34:35]
	v_pk_mul_f32 v[36:37], v[58:59], v[36:37]
	v_bfe_u32 v40, v30, 16, 1
	v_bfe_u32 v42, v27, 16, 1
	v_bfe_u32 v44, v26, 16, 1
	v_bfe_u32 v2, v31, 16, 1
	v_add3_u32 v26, v26, v44, s52
	v_add3_u32 v27, v27, v42, s52
	v_add3_u32 v30, v30, v40, s52
	v_bfe_u32 v40, v35, 16, 1
	v_bfe_u32 v42, v36, 16, 1
	v_bfe_u32 v44, v37, 16, 1
	v_add3_u32 v2, v31, v2, s52
	v_bfe_u32 v31, v34, 16, 1
	v_add3_u32 v37, v37, v44, s52
	v_add3_u32 v36, v36, v42, s52
	v_add3_u32 v35, v35, v40, s52
	v_add3_u32 v31, v34, v31, s52
	v_lshrrev_b32_e32 v34, 16, v35
	v_lshrrev_b32_e32 v35, 16, v36
	v_lshrrev_b32_e32 v36, 16, v37
	s_lshl_b32 s8, s8, 1
	v_and_or_b32 v37, v2, s53, v36
	v_or_b32_e32 v2, s14, v14
	v_lshl_add_u64 v[38:39], v[8:9], 0, s[8:9]
	v_lshrrev_b32_e32 v31, 16, v31
	v_lshlrev_b32_e32 v2, 11, v2
	v_mov_b32_e32 v46, v41
	v_and_or_b32 v36, v30, s53, v35
	v_and_or_b32 v35, v27, s53, v34
	v_and_or_b32 v34, v26, s53, v31
	v_lshl_add_u64 v[26:27], v[38:39], 0, v[2:3]
	v_pk_mul_f32 v[30:31], v[28:29], v[46:47]
	v_mov_b32_e32 v54, v51
	global_store_dwordx4 v[26:27], v[34:37], off sc1
	v_mov_b32_e32 v56, v53
	v_bfe_u32 v42, v30, 16, 1
	v_pk_mul_f32 v[34:35], v[58:59], v[54:55]
	v_mov_b32_e32 v44, v43
	v_pk_mul_f32 v[36:37], v[32:33], v[56:57]
	v_add3_u32 v30, v30, v42, s52
	v_bfe_u32 v42, v35, 16, 1
	v_pk_mul_f32 v[26:27], v[48:49], v[44:45]
	v_bfe_u32 v2, v37, 16, 1
	v_bfe_u32 v40, v36, 16, 1
	v_bfe_u32 v41, v31, 16, 1
	v_add3_u32 v35, v35, v42, s52
	v_add3_u32 v31, v31, v41, s52
	v_add3_u32 v36, v36, v40, s52
	v_add3_u32 v2, v37, v2, s52
	v_bfe_u32 v37, v26, 16, 1
	v_bfe_u32 v40, v27, 16, 1
	v_bfe_u32 v41, v34, 16, 1
	v_lshrrev_b32_e32 v35, 16, v35
	v_add3_u32 v34, v34, v41, s52
	v_add3_u32 v27, v27, v40, s52
	v_add3_u32 v26, v26, v37, s52
	v_and_or_b32 v37, v2, s53, v35
	v_or_b32_e32 v2, s14, v16
	v_lshrrev_b32_e32 v26, 16, v26
	v_lshrrev_b32_e32 v27, 16, v27
	v_lshrrev_b32_e32 v34, 16, v34
	v_lshlrev_b32_e32 v2, 11, v2
	v_and_or_b32 v36, v36, s53, v34
	v_and_or_b32 v35, v31, s53, v27
	v_and_or_b32 v34, v30, s53, v26
	v_lshl_add_u64 v[26:27], v[38:39], 0, v[2:3]
	ds_read2_b32 v[30:31], v15 offset0:16 offset1:24
	ds_read2_b32 v[40:41], v15 offset0:82 offset1:90
	global_store_dwordx4 v[26:27], v[34:37], off sc1
	ds_read2_b32 v[26:27], v15 offset0:49 offset1:57
	ds_read2_b32 v[42:43], v15 offset0:115 offset1:123
	ds_read2_b32 v[44:45], v15 offset0:148 offset1:156
	ds_read2_b32 v[46:47], v15 offset0:214 offset1:222
	ds_read2_b32 v[50:51], v15 offset0:181 offset1:189
	ds_read2_b32 v[52:53], v15 offset0:247 offset1:255
	s_waitcnt lgkmcnt(7)
	v_mov_b32_e32 v34, v30
	s_waitcnt lgkmcnt(5)
	v_mov_b32_e32 v36, v26
	s_waitcnt lgkmcnt(4)
	v_mov_b32_e32 v37, v42
	s_waitcnt lgkmcnt(3)
	v_mov_b32_e32 v54, v44
	s_waitcnt lgkmcnt(2)
	v_mov_b32_e32 v55, v46
	v_mov_b32_e32 v35, v40
	v_pk_mul_f32 v[36:37], v[28:29], v[36:37]
	v_pk_mul_f32 v[54:55], v[58:59], v[54:55]
	s_waitcnt lgkmcnt(1)
	v_mov_b32_e32 v56, v50
	s_waitcnt lgkmcnt(0)
	v_mov_b32_e32 v57, v52
	v_pk_mul_f32 v[34:35], v[48:49], v[34:35]
	v_pk_mul_f32 v[56:57], v[32:33], v[56:57]
	v_bfe_u32 v30, v37, 16, 1
	v_bfe_u32 v44, v55, 16, 1
	v_bfe_u32 v2, v57, 16, 1
	v_bfe_u32 v40, v36, 16, 1
	v_add3_u32 v30, v37, v30, s52
	v_bfe_u32 v37, v35, 16, 1
	v_add3_u32 v44, v55, v44, s52
	v_add3_u32 v40, v36, v40, s52
	v_add3_u32 v2, v57, v2, s52
	v_bfe_u32 v36, v34, 16, 1
	v_bfe_u32 v42, v54, 16, 1
	v_add3_u32 v35, v35, v37, s52
	v_lshrrev_b32_e32 v37, 16, v44
	v_bfe_u32 v26, v56, 16, 1
	v_add3_u32 v42, v54, v42, s52
	v_add3_u32 v34, v34, v36, s52
	v_and_or_b32 v37, v2, s53, v37
	v_or_b32_e32 v2, s14, v17
	v_add3_u32 v26, v56, v26, s52
	v_lshrrev_b32_e32 v34, 16, v34
	v_lshrrev_b32_e32 v35, 16, v35
	v_lshrrev_b32_e32 v36, 16, v42
	v_lshlrev_b32_e32 v2, 11, v2
	v_mov_b32_e32 v42, v27
	v_and_or_b32 v36, v26, s53, v36
	v_and_or_b32 v35, v30, s53, v35
	v_and_or_b32 v34, v40, s53, v34
	v_lshl_add_u64 v[54:55], v[38:39], 0, v[2:3]
	v_pk_mul_f32 v[26:27], v[28:29], v[42:43]
	v_mov_b32_e32 v46, v45
	global_store_dwordx4 v[54:55], v[34:37], off sc1
	v_pk_mul_f32 v[28:29], v[58:59], v[46:47]
	v_mov_b32_e32 v52, v51
	v_bfe_u32 v36, v26, 16, 1
	v_mov_b32_e32 v40, v31
	v_pk_mul_f32 v[32:33], v[32:33], v[52:53]
	v_add3_u32 v26, v26, v36, s52
	v_bfe_u32 v36, v29, 16, 1
	v_pk_mul_f32 v[30:31], v[48:49], v[40:41]
	v_bfe_u32 v2, v33, 16, 1
	v_bfe_u32 v34, v32, 16, 1
	v_bfe_u32 v35, v27, 16, 1
	v_add3_u32 v29, v29, v36, s52
	v_add3_u32 v27, v27, v35, s52
	v_add3_u32 v32, v32, v34, s52
	v_add3_u32 v2, v33, v2, s52
	v_bfe_u32 v33, v30, 16, 1
	v_bfe_u32 v34, v31, 16, 1
	v_bfe_u32 v35, v28, 16, 1
	v_lshrrev_b32_e32 v29, 16, v29
	v_add3_u32 v28, v28, v35, s52
	v_add3_u32 v31, v31, v34, s52
	v_add3_u32 v30, v30, v33, s52
	v_and_or_b32 v29, v2, s53, v29
	v_or_b32_e32 v2, s14, v18
	v_lshrrev_b32_e32 v30, 16, v30
	v_lshrrev_b32_e32 v31, 16, v31
	v_lshrrev_b32_e32 v28, 16, v28
	v_lshlrev_b32_e32 v2, 11, v2
	v_and_or_b32 v28, v32, s53, v28
	v_and_or_b32 v27, v27, s53, v31
	v_and_or_b32 v26, v26, s53, v30
	v_lshl_add_u64 v[30:31], v[38:39], 0, v[2:3]
	global_store_dwordx4 v[30:31], v[26:29], off sc1
	s_waitcnt lgkmcnt(0)

.LBB0_969:
	s_andn2_b64 vcc, exec, s[14:15]
	s_cbranch_vccnz .LBB0_962
	s_ashr_i32 s8, s3, 31
	s_lshr_b32 s8, s8, 27
	s_add_i32 s15, s3, s8
	s_ashr_i32 s8, s15, 5
	s_lshl_b32 s14, s8, 6
	s_lshl_b32 s8, s8, 10
	v_or_b32_e32 v26, s14, v12
	s_sub_i32 s8, s4, s8
	v_ashrrev_i32_e32 v27, 31, v26
	v_add_u32_e32 v2, s8, v1
	v_lshlrev_b64 v[26:27], 12, v[26:27]
	v_lshl_add_u64 v[26:27], s[46:47], 0, v[26:27]
	v_max_i32_e32 v2, 0, v2
	v_lshl_add_u64 v[26:27], v[2:3], 2, v[26:27]
	v_add_co_u32_e32 v28, vcc, s16, v26
	s_andn2_b32 s15, s15, 31
	s_nop 0
	v_addc_co_u32_e32 v29, vcc, 0, v27, vcc
	v_add_co_u32_e32 v30, vcc, s17, v26
	s_sub_i32 s15, s3, s15
	s_nop 0
	v_addc_co_u32_e32 v31, vcc, 0, v27, vcc
	v_add_co_u32_e32 v32, vcc, s18, v26
	s_cmp_lt_i32 s15, 0
	s_nop 0
	v_addc_co_u32_e32 v33, vcc, 0, v27, vcc
	v_add_co_u32_e32 v34, vcc, s19, v26
	s_cselect_b64 s[54:55], -1, 0
	s_nop 0
	v_addc_co_u32_e32 v35, vcc, 0, v27, vcc
	v_add_co_u32_e32 v36, vcc, s20, v26
	s_ashr_i32 s15, s14, 31
	s_nop 0
	v_addc_co_u32_e32 v37, vcc, 0, v27, vcc
	v_add_co_u32_e32 v38, vcc, s21, v26
	s_nop 1
	v_addc_co_u32_e32 v39, vcc, 0, v27, vcc
	v_add_co_u32_e32 v40, vcc, s24, v26
	s_nop 1
	v_addc_co_u32_e32 v41, vcc, 0, v27, vcc
	global_load_dword v2, v[26:27], off nt
	global_load_dword v44, v[28:29], off nt
	global_load_dword v45, v[30:31], off nt
	global_load_dword v46, v[32:33], off nt
	global_load_dword v47, v[34:35], off nt
	global_load_dword v48, v[36:37], off nt
	global_load_dword v49, v[38:39], off nt
	global_load_dword v50, v[40:41], off nt
	v_add_co_u32_e32 v28, vcc, s25, v26
	s_nop 1
	v_addc_co_u32_e32 v29, vcc, 0, v27, vcc
	v_add_co_u32_e32 v30, vcc, s26, v26
	s_nop 1
	v_addc_co_u32_e32 v31, vcc, 0, v27, vcc
	v_add_co_u32_e32 v32, vcc, s27, v26
	s_nop 1
	v_addc_co_u32_e32 v33, vcc, 0, v27, vcc
	v_add_co_u32_e32 v34, vcc, s28, v26
	s_nop 1
	v_addc_co_u32_e32 v35, vcc, 0, v27, vcc
	v_add_co_u32_e32 v36, vcc, s29, v26
	s_nop 1
	v_addc_co_u32_e32 v37, vcc, 0, v27, vcc
	v_add_co_u32_e32 v38, vcc, s30, v26
	s_nop 1
	v_addc_co_u32_e32 v39, vcc, 0, v27, vcc
	v_add_co_u32_e32 v40, vcc, s31, v26
	s_nop 1
	v_addc_co_u32_e32 v41, vcc, 0, v27, vcc
	v_add_co_u32_e32 v42, vcc, s33, v26
	s_nop 1
	v_addc_co_u32_e32 v43, vcc, 0, v27, vcc
	global_load_dword v51, v[28:29], off nt
	global_load_dword v52, v[30:31], off nt
	global_load_dword v53, v[32:33], off nt
	global_load_dword v54, v[34:35], off nt
	global_load_dword v55, v[36:37], off nt
	global_load_dword v56, v[38:39], off nt
	global_load_dword v57, v[40:41], off nt
	global_load_dword v58, v[42:43], off nt
	v_add_co_u32_e32 v28, vcc, s34, v26
	s_nop 1
	v_addc_co_u32_e32 v29, vcc, 0, v27, vcc
	v_add_co_u32_e32 v30, vcc, s35, v26
	s_nop 1
	v_addc_co_u32_e32 v31, vcc, 0, v27, vcc
	v_add_co_u32_e32 v32, vcc, s36, v26
	s_nop 1
	v_addc_co_u32_e32 v33, vcc, 0, v27, vcc
	v_add_co_u32_e32 v34, vcc, s37, v26
	s_nop 1
	v_addc_co_u32_e32 v35, vcc, 0, v27, vcc
	v_add_co_u32_e32 v36, vcc, s38, v26
	s_nop 1
	v_addc_co_u32_e32 v37, vcc, 0, v27, vcc
	v_add_co_u32_e32 v38, vcc, s39, v26
	s_nop 1
	v_addc_co_u32_e32 v39, vcc, 0, v27, vcc
	v_add_co_u32_e32 v40, vcc, s40, v26
	s_nop 1
	v_addc_co_u32_e32 v41, vcc, 0, v27, vcc
	v_add_co_u32_e32 v42, vcc, s41, v26
	s_nop 1
	v_addc_co_u32_e32 v43, vcc, 0, v27, vcc
	global_load_dword v59, v[28:29], off nt
	global_load_dword v60, v[30:31], off nt
	global_load_dword v61, v[32:33], off nt
	global_load_dword v62, v[34:35], off nt
	global_load_dword v63, v[36:37], off nt
	global_load_dword v64, v[38:39], off nt
	s_nop 0
	global_load_dword v40, v[40:41], off nt
	s_nop 0
	global_load_dword v41, v[42:43], off nt
	v_add_co_u32_e32 v28, vcc, s42, v26
	s_nop 1
	v_addc_co_u32_e32 v29, vcc, 0, v27, vcc
	v_add_co_u32_e32 v30, vcc, s43, v26
	s_nop 1
	v_addc_co_u32_e32 v31, vcc, 0, v27, vcc
	v_add_co_u32_e32 v32, vcc, s44, v26
	s_nop 1
	v_addc_co_u32_e32 v33, vcc, 0, v27, vcc
	v_add_co_u32_e32 v34, vcc, s45, v26
	s_nop 1
	v_addc_co_u32_e32 v35, vcc, 0, v27, vcc
	v_add_co_u32_e32 v36, vcc, s48, v26
	s_nop 1
	v_addc_co_u32_e32 v37, vcc, 0, v27, vcc
	v_add_co_u32_e32 v38, vcc, s49, v26
	s_nop 1
	v_addc_co_u32_e32 v39, vcc, 0, v27, vcc
	global_load_dword v42, v[28:29], off nt
	s_nop 0
	global_load_dword v30, v[30:31], off nt
	s_nop 0
	global_load_dword v31, v[32:33], off nt
	s_nop 0
	global_load_dword v32, v[34:35], off nt
	global_load_dword v33, v[36:37], off nt
	s_nop 0
	global_load_dword v34, v[38:39], off nt
	v_add_co_u32_e32 v28, vcc, s50, v26
	s_nop 1
	v_addc_co_u32_e32 v29, vcc, 0, v27, vcc
	v_add_co_u32_e32 v26, vcc, s51, v26
	s_nop 1
	v_addc_co_u32_e32 v27, vcc, 0, v27, vcc
	global_load_dword v28, v[28:29], off nt
	s_nop 0
	global_load_dword v26, v[26:27], off nt
	v_cndmask_b32_e64 v27, 1.0, 0, s[54:55]
	s_waitcnt vmcnt(31)
	v_mul_f32_e32 v2, v27, v2
	s_waitcnt vmcnt(30)
	v_mul_f32_e32 v29, v27, v44
	ds_write2_b32 v13, v2, v29 offset1:66
	s_waitcnt vmcnt(29)
	v_mul_f32_e32 v2, v27, v45
	s_waitcnt vmcnt(28)
	v_mul_f32_e32 v29, v27, v46
	ds_write2_b32 v13, v2, v29 offset0:132 offset1:198
	s_waitcnt vmcnt(27)
	v_mul_f32_e32 v2, v27, v47
	s_waitcnt vmcnt(26)
	v_mul_f32_e32 v29, v27, v48
	ds_write2_b32 v19, v2, v29 offset0:8 offset1:74
	s_waitcnt vmcnt(25)
	v_mul_f32_e32 v2, v27, v49
	s_waitcnt vmcnt(24)
	v_mul_f32_e32 v29, v27, v50
	ds_write2_b32 v19, v2, v29 offset0:140 offset1:206
	s_waitcnt vmcnt(23)
	v_mul_f32_e32 v2, v27, v51
	s_waitcnt vmcnt(22)
	v_mul_f32_e32 v29, v27, v52
	ds_write2_b32 v20, v2, v29 offset0:16 offset1:82
	s_waitcnt vmcnt(21)
	v_mul_f32_e32 v2, v27, v53
	s_waitcnt vmcnt(20)
	v_mul_f32_e32 v29, v27, v54
	ds_write2_b32 v20, v2, v29 offset0:148 offset1:214
	s_waitcnt vmcnt(19)
	v_mul_f32_e32 v2, v27, v55
	s_waitcnt vmcnt(18)
	v_mul_f32_e32 v29, v27, v56
	ds_write2_b32 v21, v2, v29 offset0:24 offset1:90
	s_waitcnt vmcnt(17)
	v_mul_f32_e32 v2, v27, v57
	s_waitcnt vmcnt(16)
	v_mul_f32_e32 v29, v27, v58
	ds_write2_b32 v21, v2, v29 offset0:156 offset1:222
	v_add_u32_e32 v48, s8, v14
	v_ashrrev_i32_e32 v49, 31, v48
	v_lshlrev_b64 v[50:51], 11, v[48:49]
	s_waitcnt vmcnt(15)
	v_mul_f32_e32 v2, v27, v59
	s_waitcnt vmcnt(14)
	v_mul_f32_e32 v29, v27, v60
	ds_write2_b32 v22, v2, v29 offset0:32 offset1:98
	s_waitcnt vmcnt(13)
	v_mul_f32_e32 v2, v27, v61
	s_waitcnt vmcnt(12)
	v_mul_f32_e32 v29, v27, v62
	ds_write2_b32 v22, v2, v29 offset0:164 offset1:230
	s_waitcnt vmcnt(11)
	v_mul_f32_e32 v2, v27, v63
	s_waitcnt vmcnt(10)
	v_mul_f32_e32 v29, v27, v64
	ds_write2_b32 v23, v2, v29 offset0:40 offset1:106
	s_waitcnt vmcnt(9)
	v_mul_f32_e32 v2, v27, v40
	s_waitcnt vmcnt(8)
	v_mul_f32_e32 v29, v27, v41
	ds_write2_b32 v23, v2, v29 offset0:172 offset1:238
	s_waitcnt vmcnt(7)
	v_mul_f32_e32 v2, v27, v42
	s_waitcnt vmcnt(6)
	v_mul_f32_e32 v29, v27, v30
	ds_write2_b32 v24, v2, v29 offset0:48 offset1:114
	s_waitcnt vmcnt(5)
	v_mul_f32_e32 v2, v27, v31
	s_waitcnt vmcnt(4)
	v_mul_f32_e32 v29, v27, v32
	ds_write2_b32 v24, v2, v29 offset0:180 offset1:246
	s_waitcnt vmcnt(3)
	v_mul_f32_e32 v2, v27, v33
	s_waitcnt vmcnt(2)
	v_mul_f32_e32 v29, v27, v34
	ds_write2_b32 v25, v2, v29 offset0:56 offset1:122
	v_lshl_add_u64 v[32:33], s[14:15], 1, v[10:11]
	v_lshl_add_u64 v[50:51], v[32:33], 0, v[50:51]
	s_waitcnt vmcnt(1)
	v_mul_f32_e32 v2, v27, v28
	s_waitcnt vmcnt(0)
	v_mul_f32_e32 v26, v27, v26
	ds_write2_b32 v25, v2, v26 offset0:188 offset1:254
	s_waitcnt lgkmcnt(0)
	ds_read2_b32 v[30:31], v15 offset1:8
	ds_read2_b32 v[34:35], v15 offset0:33 offset1:41
	ds_read2_b32 v[36:37], v15 offset0:66 offset1:74
	ds_read2_b32 v[38:39], v15 offset0:99 offset1:107
	ds_read2_b32 v[40:41], v15 offset0:132 offset1:140
	s_waitcnt lgkmcnt(4)
	v_bfe_u32 v2, v30, 16, 1
	v_add3_u32 v2, v30, v2, s52
	s_waitcnt lgkmcnt(3)
	v_bfe_u32 v26, v34, 16, 1
	v_lshrrev_b32_e32 v2, 16, v2
	v_add3_u32 v26, v34, v26, s52
	ds_read2_b32 v[42:43], v15 offset0:165 offset1:173
	v_and_or_b32 v26, v26, s53, v2
	s_waitcnt lgkmcnt(3)
	v_bfe_u32 v2, v36, 16, 1
	v_add3_u32 v2, v36, v2, s52
	s_waitcnt lgkmcnt(2)
	v_bfe_u32 v27, v38, 16, 1
	ds_read2_b32 v[44:45], v15 offset0:198 offset1:206
	v_lshrrev_b32_e32 v2, 16, v2
	v_add3_u32 v27, v38, v27, s52
	ds_read2_b32 v[46:47], v15 offset0:231 offset1:239
	v_and_or_b32 v27, v27, s53, v2
	s_waitcnt lgkmcnt(3)
	v_bfe_u32 v2, v40, 16, 1
	v_add3_u32 v2, v40, v2, s52
	s_waitcnt lgkmcnt(2)
	v_bfe_u32 v28, v42, 16, 1
	v_lshrrev_b32_e32 v2, 16, v2
	v_add3_u32 v28, v42, v28, s52
	v_and_or_b32 v28, v28, s53, v2
	s_waitcnt lgkmcnt(1)
	v_bfe_u32 v2, v44, 16, 1
	v_add3_u32 v2, v44, v2, s52
	s_waitcnt lgkmcnt(0)
	v_bfe_u32 v29, v46, 16, 1
	v_lshrrev_b32_e32 v2, 16, v2
	v_add3_u32 v29, v46, v29, s52
	v_and_or_b32 v29, v29, s53, v2
	v_bfe_u32 v2, v31, 16, 1
	global_store_dwordx4 v[50:51], v[26:29], off sc1
	v_add3_u32 v2, v31, v2, s52
	v_lshrrev_b32_e32 v2, 16, v2
	v_bfe_u32 v26, v35, 16, 1
	v_add3_u32 v26, v35, v26, s52
	v_and_or_b32 v26, v26, s53, v2
	v_bfe_u32 v2, v37, 16, 1
	v_add3_u32 v2, v37, v2, s52
	v_bfe_u32 v27, v39, 16, 1
	v_lshrrev_b32_e32 v2, 16, v2
	v_add3_u32 v27, v39, v27, s52
	v_and_or_b32 v27, v27, s53, v2
	v_bfe_u32 v2, v41, 16, 1
	v_add3_u32 v2, v41, v2, s52
	v_bfe_u32 v28, v43, 16, 1
	v_lshrrev_b32_e32 v2, 16, v2
	v_add3_u32 v28, v43, v28, s52
	v_and_or_b32 v28, v28, s53, v2
	v_bfe_u32 v2, v45, 16, 1
	v_add_u32_e32 v30, 8, v48
	v_add3_u32 v2, v45, v2, s52
	v_bfe_u32 v29, v47, 16, 1
	v_ashrrev_i32_e32 v31, 31, v30
	v_lshrrev_b32_e32 v2, 16, v2
	v_add3_u32 v29, v47, v29, s52
	v_lshlrev_b64 v[30:31], 11, v[30:31]
	v_and_or_b32 v29, v29, s53, v2
	ds_read2_b32 v[34:35], v15 offset0:16 offset1:24
	v_lshl_add_u64 v[30:31], v[32:33], 0, v[30:31]
	global_store_dwordx4 v[30:31], v[26:29], off sc1
	ds_read2_b32 v[30:31], v15 offset0:49 offset1:57
	ds_read2_b32 v[36:37], v15 offset0:82 offset1:90
	ds_read2_b32 v[38:39], v15 offset0:115 offset1:123
	s_waitcnt lgkmcnt(3)
	v_bfe_u32 v2, v34, 16, 1
	v_add3_u32 v2, v34, v2, s52
	s_waitcnt lgkmcnt(2)
	v_bfe_u32 v26, v30, 16, 1
	ds_read2_b32 v[40:41], v15 offset0:148 offset1:156
	v_lshrrev_b32_e32 v2, 16, v2
	v_add3_u32 v26, v30, v26, s52
	ds_read2_b32 v[42:43], v15 offset0:181 offset1:189
	v_and_or_b32 v26, v26, s53, v2
	s_waitcnt lgkmcnt(3)
	v_bfe_u32 v2, v36, 16, 1
	v_add3_u32 v2, v36, v2, s52
	s_waitcnt lgkmcnt(2)
	v_bfe_u32 v27, v38, 16, 1
	ds_read2_b32 v[44:45], v15 offset0:214 offset1:222
	v_lshrrev_b32_e32 v2, 16, v2
	v_add3_u32 v27, v38, v27, s52
	ds_read2_b32 v[46:47], v15 offset0:247 offset1:255
	v_and_or_b32 v27, v27, s53, v2
	s_waitcnt lgkmcnt(3)
	v_bfe_u32 v2, v40, 16, 1
	v_add3_u32 v2, v40, v2, s52
	s_waitcnt lgkmcnt(2)
	v_bfe_u32 v28, v42, 16, 1
	v_lshrrev_b32_e32 v2, 16, v2
	v_add3_u32 v28, v42, v28, s52
	v_and_or_b32 v28, v28, s53, v2
	s_waitcnt lgkmcnt(1)
	v_bfe_u32 v2, v44, 16, 1
	v_add_u32_e32 v50, 16, v48
	v_add3_u32 v2, v44, v2, s52
	s_waitcnt lgkmcnt(0)
	v_bfe_u32 v29, v46, 16, 1
	v_ashrrev_i32_e32 v51, 31, v50
	v_lshrrev_b32_e32 v2, 16, v2
	v_add3_u32 v29, v46, v29, s52
	v_lshlrev_b64 v[50:51], 11, v[50:51]
	v_and_or_b32 v29, v29, s53, v2
	v_lshl_add_u64 v[50:51], v[32:33], 0, v[50:51]
	v_bfe_u32 v2, v35, 16, 1
	global_store_dwordx4 v[50:51], v[26:29], off sc1
	v_add3_u32 v2, v35, v2, s52
	v_lshrrev_b32_e32 v2, 16, v2
	v_bfe_u32 v26, v31, 16, 1
	v_add3_u32 v26, v31, v26, s52
	v_and_or_b32 v26, v26, s53, v2
	v_bfe_u32 v2, v37, 16, 1
	v_add3_u32 v2, v37, v2, s52
	v_bfe_u32 v27, v39, 16, 1
	v_lshrrev_b32_e32 v2, 16, v2
	v_add3_u32 v27, v39, v27, s52
	v_and_or_b32 v27, v27, s53, v2
	v_bfe_u32 v2, v41, 16, 1
	v_add3_u32 v2, v41, v2, s52
	v_bfe_u32 v28, v43, 16, 1
	v_lshrrev_b32_e32 v2, 16, v2
	v_add3_u32 v28, v43, v28, s52
	v_and_or_b32 v28, v28, s53, v2
	v_bfe_u32 v2, v45, 16, 1
	v_add_u32_e32 v30, 24, v48
	v_add3_u32 v2, v45, v2, s52
	v_bfe_u32 v29, v47, 16, 1
	v_ashrrev_i32_e32 v31, 31, v30
	v_lshrrev_b32_e32 v2, 16, v2
	v_add3_u32 v29, v47, v29, s52
	v_lshlrev_b64 v[30:31], 11, v[30:31]
	v_and_or_b32 v29, v29, s53, v2
	v_lshl_add_u64 v[30:31], v[32:33], 0, v[30:31]
	global_store_dwordx4 v[30:31], v[26:29], off sc1
	s_waitcnt lgkmcnt(0)
	s_branch .LBB0_962
